# address arithmetic: four loop-invariant LDS address adds hoisted out of the differential-attention pass-1 key loop
# speedup vs baseline: 1.0081x; 1.0029x over previous
; DI int otid() { int t = threadIdx.x; asm volatile("" : "+v"(t)); return t; }
; template <class T> DI T* launder(T* q) { asm volatile("" : "+s"(q)); return q; }
; DI void diff_pass(const bf16_t* Qrow, const bf16_t* Kg, const bf16_t* VTg, int qt, int q0, int t, f32x16 (&O)[4], float& lsum,
;                   bf16_t* sK, bf16_t* sV, int tid, int r, int h) {
;   bf16x8 qf[4]; load_q(qf, Qrow, h);
;   const int kt_hi = 2 * qt + 1, my_hi = (q0 + 31) >> 6;
;   float m = NEG, l = 0.f;
;   zero_o<4>(O);
;   TR_<2> kr; TR_<4> vr;
;   tload(kr, Kg, 64, tid); tload(vr, VTg, SP, tid);
; DI void diff_item(const Params& p_, const EvenBufs& eb_, int e, int b, int hh, int qt, unsigned char* smem) {
;   Params p = p_; p.ws = launder(p.ws); p.subln = launder(p.subln);
;   const EvenBufs eb = even_bufs(p.ws + OFF_BIG);
;   const int tid = otid(), lane = tid & 63, wid = tid >> 6, r = lane & 31, h = lane >> 5;
;   bf16_t* sK = (bf16_t*)smem; bf16_t* sV = sK + 64 * 72;
;   const int q0 = qt * 128 + wid * 32, t = q0 + r;
;   const bf16_t* VTg = eb.DVT + (size_t)(b * 4 + hh) * 128 * SP;
;   f32x16 O[4]; float l1, l2;
;   diff_pass(eb.DQ + ((size_t)(b * 8 + hh * 2) * S + t) * 64, eb.DK + (size_t)(b * 8 + hh * 2) * S * 64, VTg, qt, q0, t, O, l1, sK, sV, tid, r, h);
; __global__ void __launch_bounds__(256, 2) mega(Params p_in, int ph_begin, int ph_end) {
;     ...
;         for (;;) {
;           const int idx = fetch_item(ctrs + layer + 8 * rep, &s_item);
;           const int nconv = layer_conv_items(layer);
;           if (idx >= 16 + nconv + 512) break;
;           if (idx < 16) { if (pmq == 0 || pmq == 4) compress_item(p, eb, e, idx, done, smem); }
;           else if (idx < 16 + nconv) { if (pmq == 0 || pmq == 5) ffn_conv_item(p, layer, idx - 16, smem); }
;           else if (pmq == 0 || pmq == 3) { const int q = idx - 16 - nconv; diff_item(p, eb, e, (q >> 2) & 3, q & 3, 31 - (q >> 4), smem); }
.LBB0_752:
	s_or_b64 exec, exec, s[0:1]
	s_waitcnt lgkmcnt(0)
	s_barrier
	ds_read_b32 v0, v209
	s_movk_i32 s0, 0x397
	s_waitcnt lgkmcnt(0)
	v_cmp_lt_i32_e32 vcc, s0, v0
	v_readfirstlane_b32 s33, v0
	s_mov_b64 s[0:1], -1
	s_cbranch_vccnz .LBB0_749
	s_cmp_gt_i32 s33, 15
	s_cbranch_scc0 .LBB0_954
	s_cmpk_gt_u32 s33, 0x197
	s_cbranch_scc0 .LBB0_776
	s_add_i32 s0, s33, 0xfffffe68
	s_lshr_b32 s4, s0, 4
	v_readlane_b32 s70, v255, 4
	v_readlane_b32 s8, v254, 25
	s_bfe_u32 s85, s0, 0x20002
	s_and_b32 s2, s33, 3
	s_sub_i32 s5, 31, s4
	v_readlane_b32 s71, v255, 5
	v_readlane_b32 s20, v254, 37
	v_readlane_b32 s21, v254, 38
	s_mov_b64 s[0:1], s[20:21]
	s_add_u32 s74, s70, 0xa316000
	s_addc_u32 s75, s71, 0
	v_writelane_b32 v255, s0, 16
	s_add_u32 s89, s70, 0xb316000
	s_addc_u32 s90, s71, 0
	v_writelane_b32 v255, s1, 17
	v_mov_b32_e32 v171, v242
	s_lshl_b32 s0, s85, 9
	s_lshl_b32 s86, s2, 7
	s_or_b32 s0, s0, s86
	v_ashrrev_i32_e32 v0, 1, v171
	v_and_b32_e32 v0, 0xffffffe0, v0
	s_mulk_i32 s0, 0x2100
	v_and_b32_e32 v12, 31, v171
	v_lshl_add_u32 v244, s5, 7, v0
	s_add_u32 s0, s70, s0
	v_or_b32_e32 v184, v244, v12
	s_addc_u32 s1, s71, 0
	s_lshl_b32 s3, s85, 15
	s_lshl_b32 s2, s2, 13
	s_or_b32 s76, s3, s2
	s_mov_b32 s77, s81
	v_ashrrev_i32_e32 v185, 31, v184
	v_lshl_add_u64 v[0:1], v[184:185], 0, s[76:77]
	v_bfe_u32 v13, v171, 5, 1
	v_lshlrev_b64 v[0:1], 7, v[0:1]
	v_lshl_add_u64 v[0:1], s[74:75], 0, v[0:1]
	v_lshlrev_b32_e32 v2, 4, v13
	v_mov_b32_e32 v3, v33
	v_lshl_add_u64 v[0:1], v[0:1], 0, v[2:3]
	s_lshl_b32 s77, s76, 7
	flat_load_dwordx4 v[130:133], v[0:1]
	flat_load_dwordx4 v[134:137], v[0:1] offset:32
	flat_load_dwordx4 v[138:141], v[0:1] offset:64
	flat_load_dwordx4 v[142:145], v[0:1] offset:96
	v_lshlrev_b32_e32 v1, 3, v171
	s_add_u32 s2, s89, s77
	v_ashrrev_i32_e32 v0, 3, v171
	v_and_b32_e32 v170, 56, v1
	s_addc_u32 s3, s90, 0
	v_lshlrev_b32_e32 v4, 1, v170
	v_mov_b32_e32 v5, v33
	v_ashrrev_i32_e32 v1, 31, v0
	v_lshl_add_u64 v[6:7], s[2:3], 0, v[4:5]
	v_lshlrev_b64 v[196:197], 7, v[0:1]
	v_lshl_add_u64 v[8:9], v[6:7], 0, v[196:197]
	global_load_dwordx4 v[146:149], v[8:9], off
	v_add_u32_e32 v8, 32, v0
	v_ashrrev_i32_e32 v9, 31, v8
	v_lshlrev_b64 v[10:11], 7, v[8:9]
	v_lshl_add_u64 v[6:7], v[6:7], 0, v[10:11]
	global_load_dwordx4 v[150:153], v[6:7], off
	v_mov_b32_e32 v206, 0xc800
	v_mov_b32_e32 v204, 1
	s_mov_b32 s73, s97
	s_mov_b64 s[96:97], 0x2000
	s_mov_b32 s69, 0x10000
	s_mov_b32 s68, 0x8000
	s_mov_b32 s67, 0xf149f2ca
	s_movk_i32 s66, 0x2000
	s_movk_i32 s65, 0x1000
	s_movk_i32 s64, 0x400
	s_movk_i32 s92, 0x800
	s_mov_b32 s84, 0x800000
	v_lshlrev_b32_e32 v178, 3, v13
	s_lshl_b32 s87, s5, 1
	v_ashrrev_i32_e32 v245, 6, v244
	v_lshlrev_b64 v[174:175], 6, v[0:1]
	v_lshlrev_b64 v[172:173], 6, v[8:9]
	v_readlane_b32 s9, v254, 26
	v_readlane_b32 s10, v254, 27
	v_readlane_b32 s11, v254, 28
	v_readlane_b32 s12, v254, 29
	v_readlane_b32 s13, v254, 30
	v_readlane_b32 s14, v254, 31
	v_readlane_b32 s15, v254, 32
	v_readlane_b32 s16, v254, 33
	v_readlane_b32 s17, v254, 34
	v_readlane_b32 s18, v254, 35
	v_readlane_b32 s19, v254, 36
	v_readlane_b32 s22, v254, 39
	v_readlane_b32 s23, v254, 40
	v_lshl_add_u64 v[6:7], s[0:1], 0, v[4:5]
	s_mov_b64 s[0:1], 0xc316000
	v_lshl_add_u64 v[186:187], v[6:7], 0, s[0:1]
	s_movk_i32 s2, 0x2100
	v_add_u32_e32 v1, 64, v0
	v_mad_i64_i32 v[192:193], s[0:1], v1, s2, 0
	v_mad_i64_i32 v[182:183], s[0:1], v1, s2, v[186:187]
	v_add_u32_e32 v1, 0x60, v0
	v_mad_i64_i32 v[176:177], s[0:1], v0, s2, v[186:187]
	v_mad_i64_i32 v[180:181], s[0:1], v8, s2, v[186:187]
	v_mad_i64_i32 v[198:199], s[0:1], v1, s2, v[186:187]
	global_load_dwordx4 v[154:157], v[176:177], off
	global_load_dwordx4 v[158:161], v[180:181], off
	global_load_dwordx4 v[162:165], v[182:183], off
	global_load_dwordx4 v[166:169], v[198:199], off
	v_mad_i64_i32 v[188:189], s[0:1], v0, s2, 0
	v_mad_i64_i32 v[190:191], s[0:1], v8, s2, 0
	s_mov_b32 s80, 64
	v_mad_i64_i32 v[194:195], s[0:1], v1, s2, 0
	s_movk_i32 s0, 0x90
	s_nop 0
	v_mul_lo_u32 v3, v0, s0
	s_movk_i32 s0, 0x88
	v_mul_lo_u32 v5, v0, s0
	s_add_u32 s0, s70, s77
	s_addc_u32 s1, s71, 0
	s_add_u32 s0, s0, 0xb319000
	s_addc_u32 s1, s1, 0
	v_and_b32_e32 v7, 7, v171
	v_mov_b32_e32 v48, v33
	v_mov_b32_e32 v49, v33
	v_mul_u32_u24_e32 v6, 0x90, v12
	v_lshl_add_u64 v[0:1], s[0:1], 0, v[196:197]
	v_lshlrev_b32_e32 v32, 4, v7
	s_lshl_b32 s0, s4, 1
	v_mov_b32_e32 v34, v33
	v_mov_b32_e32 v35, v33
	v_mov_b32_e32 v36, v33
	v_mov_b32_e32 v37, v33
	v_mov_b32_e32 v38, v33
	v_mov_b32_e32 v39, v33
	v_mov_b32_e32 v40, v33
	v_mov_b32_e32 v41, v33
	v_mov_b32_e32 v42, v33
	v_mov_b32_e32 v43, v33
	v_mov_b32_e32 v44, v33
	v_mov_b32_e32 v45, v33
	v_mov_b32_e32 v46, v33
	v_mov_b32_e32 v47, v33
	v_mov_b64_e32 v[64:65], v[48:49]
	v_mov_b64_e32 v[80:81], v[48:49]
	v_mov_b64_e32 v[96:97], v[48:49]
	v_lshlrev_b32_e32 v243, 2, v13
	v_sub_u32_e32 v246, v2, v178
	v_mul_u32_u24_e32 v247, 0x88, v12
	v_lshl_add_u64 v[200:201], v[0:1], 0, v[32:33]
	s_sub_i32 s88, 64, s0
	s_mov_b32 s91, 0
	v_mov_b32_e32 v205, 0xf149f2ca
	v_mov_b32_e32 v179, 0
	v_add_u32_e32 v248, v4, v3
	v_add_u32_e32 v239, v4, v5
	v_add_u32_e32 v249, v2, v6
	v_mov_b64_e32 v[62:63], v[46:47]
	v_mov_b64_e32 v[60:61], v[44:45]
	v_mov_b64_e32 v[58:59], v[42:43]
	v_mov_b64_e32 v[56:57], v[40:41]
	v_mov_b64_e32 v[54:55], v[38:39]
	v_mov_b64_e32 v[52:53], v[36:37]
	v_mov_b64_e32 v[50:51], v[34:35]
	v_mov_b64_e32 v[78:79], v[46:47]
	v_mov_b64_e32 v[76:77], v[44:45]
	v_mov_b64_e32 v[74:75], v[42:43]
	v_mov_b64_e32 v[72:73], v[40:41]
	v_mov_b64_e32 v[70:71], v[38:39]
	v_mov_b64_e32 v[68:69], v[36:37]
	v_mov_b64_e32 v[66:67], v[34:35]
	v_mov_b64_e32 v[94:95], v[46:47]
	v_mov_b64_e32 v[92:93], v[44:45]
	v_mov_b64_e32 v[90:91], v[42:43]
	v_mov_b64_e32 v[88:89], v[40:41]
	v_mov_b64_e32 v[86:87], v[38:39]
	v_mov_b64_e32 v[84:85], v[36:37]
	v_mov_b64_e32 v[82:83], v[34:35]
	v_add_u32_e32 v250, 0x2400, v239
	v_add_u32_e32 v251, 0x3500, v239
	v_add_u32_e32 v252, 0x4600, v239
	v_add_u32_e32 v253, 0x5700, v239
	s_branch .LBB0_758

; template <int NV> DI void tload(TR_<NV>& t, const bf16_t* g, size_t ld, int tid) {
; #pragma unroll
;   for (int i = 0; i < NV; ++i) t.v[i] = gload16(g + (size_t)((tid >> 3) + 32 * i) * ld + (tid & 7) * 8);
;   __builtin_amdgcn_sched_barrier(0);
; }
; template <int NV> DI void tstore72(const TR_<NV>& t, bf16_t* s, int tid) {
; #pragma unroll
;   for (int i = 0; i < NV; ++i) *(u32x4*)(s + ((tid >> 3) + 32 * i) * 72 + (tid & 7) * 8) = t.v[i];
; }
; template <int NV> DI void tstore68(const TR_<NV>& t, bf16_t* s, int tid) {
; #pragma unroll
;   for (int i = 0; i < NV; ++i) {
;     bf16_t* d = s + ((tid >> 3) + 32 * i) * 68 + (tid & 7) * 8;
;     *(u32x2*)d = (u32x2){t.v[i].x, t.v[i].y};
;     *(u32x2*)(d + 4) = (u32x2){t.v[i].z, t.v[i].w};
;   }
; }
; DI void diff_pass(const bf16_t* Qrow, const bf16_t* Kg, const bf16_t* VTg, int qt, int q0, int t, f32x16 (&O)[4], float& lsum,
;                   bf16_t* sK, bf16_t* sV, int tid, int r, int h) {
;     ...
;   for (int kt = 0; kt <= kt_hi; ++kt) {
;     __syncthreads();
;     tstore72(kr, sK, tid); tstore68(vr, sV, tid);
;     __syncthreads();
;     if (kt < kt_hi) { tload(kr, Kg + (size_t)(kt + 1) * 64 * 64, 64, tid); tload(vr, VTg + (kt + 1) * 64, SP, tid); }
.LBB0_758:
	s_cmp_gt_u32 s91, s87
	s_waitcnt lgkmcnt(0)
	s_barrier
	s_waitcnt vmcnt(0)
	ds_write_b128 v248, v[146:149]
	ds_write_b128 v248, v[150:153] offset:4608
	ds_write2_b64 v250, v[154:155], v[156:157] offset1:1
	ds_write2_b64 v251, v[158:159], v[160:161] offset1:1
	ds_write2_b64 v252, v[162:163], v[164:165] offset1:1
	ds_write2_b64 v253, v[166:167], v[168:169] offset1:1
	s_waitcnt lgkmcnt(0)
	s_barrier
	s_cbranch_scc1 .LBB0_760
	global_load_dwordx4 v[146:149], v[200:201], off offset:-4096
	global_load_dwordx4 v[150:153], v[200:201], off
	v_lshl_add_u64 v[0:1], s[80:81], 1, v[186:187]
	v_lshl_add_u64 v[2:3], v[0:1], 0, v[188:189]
	global_load_dwordx4 v[154:157], v[2:3], off
	v_lshl_add_u64 v[2:3], v[0:1], 0, v[190:191]
	global_load_dwordx4 v[158:161], v[2:3], off
	v_lshl_add_u64 v[2:3], v[0:1], 0, v[192:193]
	v_lshl_add_u64 v[0:1], v[0:1], 0, v[194:195]
	global_load_dwordx4 v[162:165], v[2:3], off
	global_load_dwordx4 v[166:169], v[0:1], off
